# v21 plus: per-query softmax butterflies steps 1,2,4,8 as DPP moves instead of ds_bpermute; block lgkmcnt waits recomputed
# baseline (speedup 1.0000x reference)
.LBB0_2228:
	v_and_b32_e32 v9, 64, v217
	v_add_u32_e32 v17, 64, v9
	v_max_f32_e32 v9, v138, v138
	v_max_f32_e32 v10, v137, v137
	v_max_f32_e32 v9, v10, v9
	v_xor_b32_e32 v10, 1, v217
	v_max3_f32 v9, v9, v139, v140
	v_cmp_lt_i32_e64 s[8:9], v10, v17
	v_max3_f32 v9, v9, v86, v87
	v_max3_f32 v9, v9, v88, v18
	v_cndmask_b32_e64 v10, v217, v10, s[8:9]
	v_lshlrev_b32_e32 v70, 2, v10
	v_mov_b32_dpp v10, v9 quad_perm:[1,0,3,2] row_mask:0xf bank_mask:0xf
	v_max_f32_e32 v21, v136, v136
	v_max_f32_e32 v22, v135, v135
	v_max_f32_e32 v21, v22, v21
	v_max3_f32 v21, v21, v133, v134
	s_waitcnt lgkmcnt(0)
	v_max_f32_e32 v10, v10, v10
	v_max_f32_e32 v9, v9, v10
	v_xor_b32_e32 v10, 2, v217
	v_cmp_lt_i32_e64 s[8:9], v10, v17
	v_max3_f32 v21, v21, v83, v84
	v_max3_f32 v21, v21, v85, v19
	v_cndmask_b32_e64 v10, v217, v10, s[8:9]
	v_lshlrev_b32_e32 v71, 2, v10
	v_mov_b32_dpp v10, v9 quad_perm:[2,3,0,1] row_mask:0xf bank_mask:0xf
	v_mov_b32_dpp v22, v21 quad_perm:[1,0,3,2] row_mask:0xf bank_mask:0xf
	v_xor_b32_e32 v23, 32, v217
	v_max_f32_e32 v29, v33, v33
	s_waitcnt lgkmcnt(0)
	v_max_f32_e32 v10, v10, v10
	v_max_f32_e32 v9, v9, v10
	v_xor_b32_e32 v10, 4, v217
	v_cmp_lt_i32_e64 s[8:9], v10, v17
	s_waitcnt lgkmcnt(0)
	v_max_f32_e32 v22, v22, v22
	v_max_f32_e32 v21, v21, v22
	v_cndmask_b32_e64 v10, v217, v10, s[8:9]
	v_lshlrev_b32_e32 v72, 2, v10
	v_mov_b32_dpp v10, v9 row_half_mirror row_mask:0xf bank_mask:0xf
	v_mov_b32_dpp v22, v21 quad_perm:[2,3,0,1] row_mask:0xf bank_mask:0xf
	s_waitcnt lgkmcnt(0)
	v_max_f32_e32 v10, v10, v10
	v_max_f32_e32 v9, v9, v10
	v_xor_b32_e32 v10, 8, v217
	v_cmp_lt_i32_e64 s[8:9], v10, v17
	s_waitcnt lgkmcnt(0)
	v_max_f32_e32 v22, v22, v22
	v_max_f32_e32 v21, v21, v22
	v_cndmask_b32_e64 v10, v217, v10, s[8:9]
	v_lshlrev_b32_e32 v73, 2, v10
	v_mov_b32_dpp v10, v9 row_mirror row_mask:0xf bank_mask:0xf
	v_mov_b32_dpp v22, v21 row_half_mirror row_mask:0xf bank_mask:0xf
	s_waitcnt lgkmcnt(0)
	v_max_f32_e32 v10, v10, v10
	v_max_f32_e32 v9, v9, v10
	v_xor_b32_e32 v10, 16, v217
	v_cmp_lt_i32_e64 s[8:9], v10, v17
	s_waitcnt lgkmcnt(0)
	v_max_f32_e32 v22, v22, v22
	v_max_f32_e32 v21, v21, v22
	v_cndmask_b32_e64 v10, v217, v10, s[8:9]
	v_lshlrev_b32_e32 v74, 2, v10
	ds_bpermute_b32 v10, v74, v9
	v_mov_b32_dpp v22, v21 row_mirror row_mask:0xf bank_mask:0xf
	s_waitcnt lgkmcnt(0)
	v_max_f32_e32 v10, v10, v10
	v_max_f32_e32 v9, v9, v10
	v_cmp_neq_f32_e64 s[8:9], s39, v9
	s_waitcnt lgkmcnt(0)
	v_max_f32_e32 v22, v22, v22
	v_max_f32_e32 v21, v21, v22
	v_cndmask_b32_e64 v16, 0, v9, s[8:9]
	v_sub_f32_e32 v9, v137, v16
	v_exp_f32_e32 v9, v9
	v_sub_f32_e32 v10, v138, v16
	v_exp_f32_e32 v10, v10
	v_sub_f32_e32 v11, v139, v16
	v_exp_f32_e32 v11, v11
	v_sub_f32_e32 v12, v140, v16
	v_exp_f32_e32 v12, v12
	v_add_f32_e32 v13, 0, v9
	v_add_f32_e32 v13, v10, v13
	v_add_f32_e32 v13, v11, v13
	v_add_f32_e32 v20, v12, v13
	v_sub_f32_e32 v13, v86, v16
	v_exp_f32_e32 v13, v13
	v_sub_f32_e32 v14, v87, v16
	v_exp_f32_e32 v14, v14
	v_sub_f32_e32 v15, v88, v16
	v_exp_f32_e32 v15, v15
	v_sub_f32_e32 v16, v18, v16
	v_exp_f32_e32 v16, v16
	v_add_f32_e32 v18, v13, v20
	v_add_f32_e32 v18, v14, v18
	v_add_f32_e32 v18, v15, v18
	v_add_f32_e32 v18, v16, v18
	s_nop 1
	v_mov_b32_dpp v20, v18 quad_perm:[1,0,3,2] row_mask:0xf bank_mask:0xf
	ds_bpermute_b32 v22, v74, v21
	v_cmp_lt_i32_e64 s[8:9], v23, v17
	s_waitcnt lgkmcnt(1)
	v_add_f32_e32 v18, v18, v20
	s_nop 1
	v_mov_b32_dpp v20, v18 quad_perm:[2,3,0,1] row_mask:0xf bank_mask:0xf
	v_cndmask_b32_e64 v17, v217, v23, s[8:9]
	v_lshlrev_b32_e32 v75, 2, v17
	s_waitcnt lgkmcnt(0)
	v_max_f32_e32 v17, v22, v22
	v_max_f32_e32 v17, v21, v17
	s_waitcnt lgkmcnt(0)
	v_add_f32_e32 v18, v18, v20
	s_nop 1
	v_mov_b32_dpp v20, v18 row_half_mirror row_mask:0xf bank_mask:0xf
	v_max_f32_e32 v21, v130, v130
	v_cmp_neq_f32_e64 s[8:9], s39, v17
	s_waitcnt lgkmcnt(0)
	v_add_f32_e32 v18, v18, v20
	s_nop 1
	v_mov_b32_dpp v20, v18 row_mirror row_mask:0xf bank_mask:0xf
	v_cndmask_b32_e64 v25, 0, v17, s[8:9]
	v_sub_f32_e32 v17, v135, v25
	v_exp_f32_e32 v17, v17
	v_sub_f32_e32 v19, v19, v25
	s_waitcnt lgkmcnt(0)
	v_add_f32_e32 v18, v18, v20
	ds_bpermute_b32 v20, v74, v18
	v_add_f32_e32 v24, 0, v17
	v_exp_f32_e32 v19, v19
	s_waitcnt lgkmcnt(0)
	v_add_f32_e32 v68, v18, v20
	v_max_f32_e32 v20, v131, v131
	v_max_f32_e32 v20, v21, v20
	v_max3_f32 v20, v20, v132, v129
	v_max3_f32 v20, v20, v82, v6
	v_max3_f32 v22, v20, v7, v8
	s_nop 1
	v_mov_b32_dpp v23, v22 quad_perm:[1,0,3,2] row_mask:0xf bank_mask:0xf
	v_sub_f32_e32 v18, v136, v25
	v_exp_f32_e32 v18, v18
	v_sub_f32_e32 v20, v133, v25
	v_exp_f32_e32 v21, v20
	s_waitcnt lgkmcnt(0)
	v_max_f32_e32 v23, v23, v23
	v_max_f32_e32 v22, v22, v23
	s_nop 1
	v_mov_b32_dpp v23, v22 quad_perm:[2,3,0,1] row_mask:0xf bank_mask:0xf
	v_sub_f32_e32 v20, v134, v25
	v_exp_f32_e32 v20, v20
	v_add_f32_e32 v24, v18, v24
	v_add_f32_e32 v24, v21, v24
	s_waitcnt lgkmcnt(0)
	v_max_f32_e32 v23, v23, v23
	v_add_f32_e32 v26, v20, v24
	v_max_f32_e32 v24, v22, v23
	s_nop 1
	v_mov_b32_dpp v27, v24 row_half_mirror row_mask:0xf bank_mask:0xf
	v_sub_f32_e32 v22, v83, v25
	v_exp_f32_e32 v23, v22
	v_sub_f32_e32 v22, v84, v25
	v_exp_f32_e32 v22, v22
	s_waitcnt lgkmcnt(0)
	v_max_f32_e32 v27, v27, v27
	v_max_f32_e32 v27, v24, v27
	s_nop 1
	v_mov_b32_dpp v28, v27 row_mirror row_mask:0xf bank_mask:0xf
	v_sub_f32_e32 v24, v85, v25
	v_exp_f32_e32 v24, v24
	v_add_f32_e32 v26, v23, v26
	v_add_f32_e32 v26, v22, v26
	s_waitcnt lgkmcnt(0)
	v_max_f32_e32 v25, v28, v28
	v_max_f32_e32 v28, v126, v126
	v_max_f32_e32 v28, v29, v28
	v_max3_f32 v28, v28, v127, v128
	v_max3_f32 v28, v28, v2, v3
	v_max3_f32 v28, v28, v4, v5
	v_max_f32_e32 v25, v27, v25
	s_nop 0
	v_mov_b32_dpp v29, v28 quad_perm:[1,0,3,2] row_mask:0xf bank_mask:0xf
	ds_bpermute_b32 v27, v74, v25
	v_add_f32_e32 v26, v24, v26
	v_add_f32_e32 v77, v19, v26
	s_nop 1
	v_mov_b32_dpp v78, v77 quad_perm:[1,0,3,2] row_mask:0xf bank_mask:0xf
	s_waitcnt lgkmcnt(1)
	v_max_f32_e32 v29, v29, v29
	s_waitcnt lgkmcnt(0)
	v_max_f32_e32 v26, v27, v27
	v_max_f32_e32 v76, v28, v29
	v_max_f32_e32 v25, v25, v26
	s_nop 0
	v_mov_b32_dpp v79, v76 quad_perm:[2,3,0,1] row_mask:0xf bank_mask:0xf
	v_cmp_neq_f32_e64 s[8:9], s39, v25
	s_waitcnt lgkmcnt(0)
	v_add_f32_e32 v77, v77, v78
	s_nop 1
	v_mov_b32_dpp v78, v77 quad_perm:[2,3,0,1] row_mask:0xf bank_mask:0xf
	v_cndmask_b32_e64 v67, 0, v25, s[8:9]
	v_sub_f32_e32 v25, v130, v67
	v_exp_f32_e32 v25, v25
	v_sub_f32_e32 v26, v131, v67
	v_exp_f32_e32 v26, v26
	v_sub_f32_e32 v27, v132, v67
	s_waitcnt lgkmcnt(0)
	v_max_f32_e32 v79, v79, v79
	v_exp_f32_e32 v27, v27
	v_sub_f32_e32 v28, v129, v67
	v_max_f32_e32 v76, v76, v79
	v_exp_f32_e32 v29, v28
	v_sub_f32_e32 v28, v82, v67
	v_mov_b32_dpp v79, v76 row_half_mirror row_mask:0xf bank_mask:0xf
	v_add_f32_e32 v66, 0, v25
	v_exp_f32_e32 v28, v28
	v_add_f32_e32 v66, v26, v66
	v_add_f32_e32 v66, v27, v66
	v_add_f32_e32 v66, v29, v66
	v_add_f32_e32 v80, v28, v66
	s_waitcnt lgkmcnt(0)
	v_max_f32_e32 v66, v79, v79
	v_max_f32_e32 v76, v76, v66
	s_nop 1
	v_mov_b32_dpp v79, v76 row_mirror row_mask:0xf bank_mask:0xf
	v_sub_f32_e32 v7, v7, v67
	v_exp_f32_e32 v66, v7
	v_sub_f32_e32 v7, v8, v67
	v_sub_f32_e32 v6, v6, v67
	s_waitcnt lgkmcnt(0)
	v_max_f32_e32 v8, v79, v79
	v_max_f32_e32 v8, v76, v8
	ds_bpermute_b32 v67, v74, v8
	v_exp_f32_e32 v6, v6
	v_exp_f32_e32 v7, v7
	v_add_f32_e32 v77, v77, v78
	s_nop 1
	v_mov_b32_dpp v78, v77 row_half_mirror row_mask:0xf bank_mask:0xf
	s_waitcnt lgkmcnt(0)
	v_max_f32_e32 v67, v67, v67
	v_max_f32_e32 v8, v8, v67
	v_cmp_neq_f32_e64 s[8:9], s39, v8
	v_add_f32_e32 v76, v6, v80
	v_add_f32_e32 v76, v66, v76
	v_cndmask_b32_e64 v81, 0, v8, s[8:9]
	v_sub_f32_e32 v8, v33, v81
	v_exp_f32_e32 v8, v8
	v_sub_f32_e32 v33, v126, v81
	v_exp_f32_e32 v33, v33
	v_sub_f32_e32 v67, v127, v81
	v_add_f32_e32 v79, v7, v76
	v_exp_f32_e32 v67, v67
	v_sub_f32_e32 v76, v128, v81
	v_exp_f32_e32 v76, v76
	v_sub_f32_e32 v2, v2, v81
	v_add_f32_e32 v82, 0, v8
	v_exp_f32_e32 v2, v2
	v_sub_f32_e32 v3, v3, v81
	v_add_f32_e32 v82, v33, v82
	v_exp_f32_e32 v3, v3
	v_sub_f32_e32 v4, v4, v81
	v_add_f32_e32 v82, v67, v82
	v_exp_f32_e32 v4, v4
	v_sub_f32_e32 v5, v5, v81
	v_add_f32_e32 v82, v76, v82
	v_exp_f32_e32 v5, v5
	v_add_f32_e32 v81, v2, v82
	v_add_f32_e32 v81, v3, v81
	v_add_f32_e32 v81, v4, v81
	v_add_f32_e32 v81, v5, v81
	v_mov_b32_dpp v80, v79 quad_perm:[1,0,3,2] row_mask:0xf bank_mask:0xf
	s_nop 0
	v_mov_b32_dpp v70, v81 quad_perm:[1,0,3,2] row_mask:0xf bank_mask:0xf
	ds_bpermute_b32 v69, v75, v68
	s_waitcnt lgkmcnt(1)
	v_add_f32_e32 v79, v79, v80
	s_waitcnt lgkmcnt(1)
	v_add_f32_e32 v70, v81, v70
	v_mov_b32_dpp v80, v79 quad_perm:[2,3,0,1] row_mask:0xf bank_mask:0xf
	s_nop 0
	v_mov_b32_dpp v71, v70 quad_perm:[2,3,0,1] row_mask:0xf bank_mask:0xf
	s_waitcnt lgkmcnt(0)
	v_add_f32_e32 v79, v79, v80
	s_waitcnt lgkmcnt(0)
	v_add_f32_e32 v70, v70, v71
	v_mov_b32_dpp v80, v79 row_half_mirror row_mask:0xf bank_mask:0xf
	s_nop 0
	v_mov_b32_dpp v71, v70 row_half_mirror row_mask:0xf bank_mask:0xf
	v_add_f32_e32 v72, v77, v78
	s_nop 1
	v_mov_b32_dpp v77, v72 row_mirror row_mask:0xf bank_mask:0xf
	s_waitcnt lgkmcnt(0)
	v_add_f32_e32 v78, v79, v80
	s_waitcnt lgkmcnt(0)
	v_add_f32_e32 v70, v70, v71
	v_mov_b32_dpp v79, v78 row_mirror row_mask:0xf bank_mask:0xf
	s_nop 0
	v_mov_b32_dpp v71, v70 row_mirror row_mask:0xf bank_mask:0xf
	s_waitcnt lgkmcnt(0)
	v_add_f32_e32 v72, v72, v77
	ds_bpermute_b32 v73, v74, v72
	s_waitcnt lgkmcnt(1)
	v_add_f32_e32 v77, v78, v79
	s_waitcnt lgkmcnt(1)
	v_add_f32_e32 v79, v70, v71
	ds_bpermute_b32 v78, v74, v77
	ds_bpermute_b32 v74, v74, v79
	s_waitcnt lgkmcnt(2)
	v_add_f32_e32 v70, v72, v73
	ds_bpermute_b32 v71, v75, v70
	s_waitcnt lgkmcnt(2)
	v_add_f32_e32 v72, v77, v78
	s_waitcnt lgkmcnt(1)
	v_add_f32_e32 v74, v79, v74
	ds_bpermute_b32 v73, v75, v72
	ds_bpermute_b32 v75, v75, v74
	s_and_saveexec_b64 s[8:9], s[6:7]
	s_cbranch_execz .LBB0_2230
	v_readlane_b32 s3, v255, 22
	v_cvt_pk_bf16_f32 v9, v9, v149
	s_nop 1
	v_lshl_add_u32 v77, v30, 1, s3
	ds_write_b16 v77, v9
	v_cvt_pk_bf16_f32 v9, v10, v149
	ds_write_b16 v77, v9 offset:64
	v_cvt_pk_bf16_f32 v9, v11, v149
	ds_write_b16 v77, v9 offset:128
	v_cvt_pk_bf16_f32 v9, v12, v149
	ds_write_b16 v77, v9 offset:192
	v_cvt_pk_bf16_f32 v9, v13, v149
	ds_write_b16 v77, v9 offset:256
	v_cvt_pk_bf16_f32 v9, v14, v149
	ds_write_b16 v77, v9 offset:320
	v_cvt_pk_bf16_f32 v9, v15, v149
	ds_write_b16 v77, v9 offset:384
	v_cvt_pk_bf16_f32 v9, v16, v149
	ds_write_b16 v77, v9 offset:448
	v_cvt_pk_bf16_f32 v9, v17, v149
	ds_write_b16 v77, v9 offset:512
	v_cvt_pk_bf16_f32 v9, v18, v149
	ds_write_b16 v77, v9 offset:576
	v_cvt_pk_bf16_f32 v9, v21, v149
	ds_write_b16 v77, v9 offset:640
	v_cvt_pk_bf16_f32 v9, v20, v149
	ds_write_b16 v77, v9 offset:704
	v_cvt_pk_bf16_f32 v9, v23, v149
	ds_write_b16 v77, v9 offset:768
	v_cvt_pk_bf16_f32 v9, v22, v149
	ds_write_b16 v77, v9 offset:832
	v_cvt_pk_bf16_f32 v9, v24, v149
	ds_write_b16 v77, v9 offset:896
	v_cvt_pk_bf16_f32 v9, v19, v149
	ds_write_b16 v77, v9 offset:960
	v_cvt_pk_bf16_f32 v9, v25, v149
	ds_write_b16 v77, v9 offset:1024
	v_cvt_pk_bf16_f32 v9, v26, v149
	ds_write_b16 v77, v9 offset:1088
	v_cvt_pk_bf16_f32 v9, v27, v149
	ds_write_b16 v77, v9 offset:1152
	v_cvt_pk_bf16_f32 v9, v29, v149
	ds_write_b16 v77, v9 offset:1216
	v_cvt_pk_bf16_f32 v9, v28, v149
	ds_write_b16 v77, v9 offset:1280
	v_cvt_pk_bf16_f32 v6, v6, v149
	ds_write_b16 v77, v6 offset:1344
	v_cvt_pk_bf16_f32 v6, v66, v149
	ds_write_b16 v77, v6 offset:1408
	v_cvt_pk_bf16_f32 v6, v7, v149
	ds_write_b16 v77, v6 offset:1472
	v_cvt_pk_bf16_f32 v6, v8, v149
	ds_write_b16 v77, v6 offset:1536
	v_cvt_pk_bf16_f32 v6, v33, v149
	ds_write_b16 v77, v6 offset:1600
	v_cvt_pk_bf16_f32 v6, v67, v149
	ds_write_b16 v77, v6 offset:1664
	v_cvt_pk_bf16_f32 v6, v76, v149
	ds_write_b16 v77, v6 offset:1728
	v_cvt_pk_bf16_f32 v2, v2, v149
	ds_write_b16 v77, v2 offset:1792
	v_cvt_pk_bf16_f32 v2, v3, v149
	ds_write_b16 v77, v2 offset:1856
	v_cvt_pk_bf16_f32 v2, v4, v149
	ds_write_b16 v77, v2 offset:1920
	v_cvt_pk_bf16_f32 v2, v5, v149
	ds_write_b16 v77, v2 offset:1984

.LBB0_4487:
	v_and_b32_e32 v9, 64, v217
	v_add_u32_e32 v17, 64, v9
	v_max_f32_e32 v9, v138, v138
	v_max_f32_e32 v10, v137, v137
	v_max_f32_e32 v9, v10, v9
	v_xor_b32_e32 v10, 1, v217
	v_max3_f32 v9, v9, v139, v140
	v_cmp_lt_i32_e64 s[8:9], v10, v17
	v_max3_f32 v9, v9, v86, v87
	v_max3_f32 v9, v9, v88, v18
	v_cndmask_b32_e64 v10, v217, v10, s[8:9]
	v_lshlrev_b32_e32 v70, 2, v10
	v_mov_b32_dpp v10, v9 quad_perm:[1,0,3,2] row_mask:0xf bank_mask:0xf
	v_max_f32_e32 v21, v136, v136
	v_max_f32_e32 v22, v135, v135
	v_max_f32_e32 v21, v22, v21
	v_max3_f32 v21, v21, v133, v134
	s_waitcnt lgkmcnt(0)
	v_max_f32_e32 v10, v10, v10
	v_max_f32_e32 v9, v9, v10
	v_xor_b32_e32 v10, 2, v217
	v_cmp_lt_i32_e64 s[8:9], v10, v17
	v_max3_f32 v21, v21, v83, v84
	v_max3_f32 v21, v21, v85, v19
	v_cndmask_b32_e64 v10, v217, v10, s[8:9]
	v_lshlrev_b32_e32 v71, 2, v10
	v_mov_b32_dpp v10, v9 quad_perm:[2,3,0,1] row_mask:0xf bank_mask:0xf
	v_mov_b32_dpp v22, v21 quad_perm:[1,0,3,2] row_mask:0xf bank_mask:0xf
	v_xor_b32_e32 v23, 32, v217
	v_max_f32_e32 v29, v33, v33
	s_waitcnt lgkmcnt(0)
	v_max_f32_e32 v10, v10, v10
	v_max_f32_e32 v9, v9, v10
	v_xor_b32_e32 v10, 4, v217
	v_cmp_lt_i32_e64 s[8:9], v10, v17
	s_waitcnt lgkmcnt(0)
	v_max_f32_e32 v22, v22, v22
	v_max_f32_e32 v21, v21, v22
	v_cndmask_b32_e64 v10, v217, v10, s[8:9]
	v_lshlrev_b32_e32 v72, 2, v10
	v_mov_b32_dpp v10, v9 row_half_mirror row_mask:0xf bank_mask:0xf
	v_mov_b32_dpp v22, v21 quad_perm:[2,3,0,1] row_mask:0xf bank_mask:0xf
	s_waitcnt lgkmcnt(0)
	v_max_f32_e32 v10, v10, v10
	v_max_f32_e32 v9, v9, v10
	v_xor_b32_e32 v10, 8, v217
	v_cmp_lt_i32_e64 s[8:9], v10, v17
	s_waitcnt lgkmcnt(0)
	v_max_f32_e32 v22, v22, v22
	v_max_f32_e32 v21, v21, v22
	v_cndmask_b32_e64 v10, v217, v10, s[8:9]
	v_lshlrev_b32_e32 v73, 2, v10
	v_mov_b32_dpp v10, v9 row_mirror row_mask:0xf bank_mask:0xf
	v_mov_b32_dpp v22, v21 row_half_mirror row_mask:0xf bank_mask:0xf
	s_waitcnt lgkmcnt(0)
	v_max_f32_e32 v10, v10, v10
	v_max_f32_e32 v9, v9, v10
	v_xor_b32_e32 v10, 16, v217
	v_cmp_lt_i32_e64 s[8:9], v10, v17
	s_waitcnt lgkmcnt(0)
	v_max_f32_e32 v22, v22, v22
	v_max_f32_e32 v21, v21, v22
	v_cndmask_b32_e64 v10, v217, v10, s[8:9]
	v_lshlrev_b32_e32 v74, 2, v10
	ds_bpermute_b32 v10, v74, v9
	v_mov_b32_dpp v22, v21 row_mirror row_mask:0xf bank_mask:0xf
	s_waitcnt lgkmcnt(0)
	v_max_f32_e32 v10, v10, v10
	v_max_f32_e32 v9, v9, v10
	v_cmp_neq_f32_e64 s[8:9], s39, v9
	s_waitcnt lgkmcnt(0)
	v_max_f32_e32 v22, v22, v22
	v_max_f32_e32 v21, v21, v22
	v_cndmask_b32_e64 v16, 0, v9, s[8:9]
	v_sub_f32_e32 v9, v137, v16
	v_exp_f32_e32 v9, v9
	v_sub_f32_e32 v10, v138, v16
	v_exp_f32_e32 v10, v10
	v_sub_f32_e32 v11, v139, v16
	v_exp_f32_e32 v11, v11
	v_sub_f32_e32 v12, v140, v16
	v_exp_f32_e32 v12, v12
	v_add_f32_e32 v13, 0, v9
	v_add_f32_e32 v13, v10, v13
	v_add_f32_e32 v13, v11, v13
	v_add_f32_e32 v20, v12, v13
	v_sub_f32_e32 v13, v86, v16
	v_exp_f32_e32 v13, v13
	v_sub_f32_e32 v14, v87, v16
	v_exp_f32_e32 v14, v14
	v_sub_f32_e32 v15, v88, v16
	v_exp_f32_e32 v15, v15
	v_sub_f32_e32 v16, v18, v16
	v_exp_f32_e32 v16, v16
	v_add_f32_e32 v18, v13, v20
	v_add_f32_e32 v18, v14, v18
	v_add_f32_e32 v18, v15, v18
	v_add_f32_e32 v18, v16, v18
	s_nop 1
	v_mov_b32_dpp v20, v18 quad_perm:[1,0,3,2] row_mask:0xf bank_mask:0xf
	ds_bpermute_b32 v22, v74, v21
	v_cmp_lt_i32_e64 s[8:9], v23, v17
	s_waitcnt lgkmcnt(1)
	v_add_f32_e32 v18, v18, v20
	s_nop 1
	v_mov_b32_dpp v20, v18 quad_perm:[2,3,0,1] row_mask:0xf bank_mask:0xf
	v_cndmask_b32_e64 v17, v217, v23, s[8:9]
	v_lshlrev_b32_e32 v75, 2, v17
	s_waitcnt lgkmcnt(0)
	v_max_f32_e32 v17, v22, v22
	v_max_f32_e32 v17, v21, v17
	s_waitcnt lgkmcnt(0)
	v_add_f32_e32 v18, v18, v20
	s_nop 1
	v_mov_b32_dpp v20, v18 row_half_mirror row_mask:0xf bank_mask:0xf
	v_max_f32_e32 v21, v130, v130
	v_cmp_neq_f32_e64 s[8:9], s39, v17
	s_waitcnt lgkmcnt(0)
	v_add_f32_e32 v18, v18, v20
	s_nop 1
	v_mov_b32_dpp v20, v18 row_mirror row_mask:0xf bank_mask:0xf
	v_cndmask_b32_e64 v25, 0, v17, s[8:9]
	v_sub_f32_e32 v17, v135, v25
	v_exp_f32_e32 v17, v17
	v_sub_f32_e32 v19, v19, v25
	s_waitcnt lgkmcnt(0)
	v_add_f32_e32 v18, v18, v20
	ds_bpermute_b32 v20, v74, v18
	v_add_f32_e32 v24, 0, v17
	v_exp_f32_e32 v19, v19
	s_waitcnt lgkmcnt(0)
	v_add_f32_e32 v68, v18, v20
	v_max_f32_e32 v20, v131, v131
	v_max_f32_e32 v20, v21, v20
	v_max3_f32 v20, v20, v132, v129
	v_max3_f32 v20, v20, v82, v6
	v_max3_f32 v22, v20, v7, v8
	s_nop 1
	v_mov_b32_dpp v23, v22 quad_perm:[1,0,3,2] row_mask:0xf bank_mask:0xf
	v_sub_f32_e32 v18, v136, v25
	v_exp_f32_e32 v18, v18
	v_sub_f32_e32 v20, v133, v25
	v_exp_f32_e32 v21, v20
	s_waitcnt lgkmcnt(0)
	v_max_f32_e32 v23, v23, v23
	v_max_f32_e32 v22, v22, v23
	s_nop 1
	v_mov_b32_dpp v23, v22 quad_perm:[2,3,0,1] row_mask:0xf bank_mask:0xf
	v_sub_f32_e32 v20, v134, v25
	v_exp_f32_e32 v20, v20
	v_add_f32_e32 v24, v18, v24
	v_add_f32_e32 v24, v21, v24
	s_waitcnt lgkmcnt(0)
	v_max_f32_e32 v23, v23, v23
	v_add_f32_e32 v26, v20, v24
	v_max_f32_e32 v24, v22, v23
	s_nop 1
	v_mov_b32_dpp v27, v24 row_half_mirror row_mask:0xf bank_mask:0xf
	v_sub_f32_e32 v22, v83, v25
	v_exp_f32_e32 v23, v22
	v_sub_f32_e32 v22, v84, v25
	v_exp_f32_e32 v22, v22
	s_waitcnt lgkmcnt(0)
	v_max_f32_e32 v27, v27, v27
	v_max_f32_e32 v27, v24, v27
	s_nop 1
	v_mov_b32_dpp v28, v27 row_mirror row_mask:0xf bank_mask:0xf
	v_sub_f32_e32 v24, v85, v25
	v_exp_f32_e32 v24, v24
	v_add_f32_e32 v26, v23, v26
	v_add_f32_e32 v26, v22, v26
	s_waitcnt lgkmcnt(0)
	v_max_f32_e32 v25, v28, v28
	v_max_f32_e32 v28, v126, v126
	v_max_f32_e32 v28, v29, v28
	v_max3_f32 v28, v28, v127, v128
	v_max3_f32 v28, v28, v2, v3
	v_max3_f32 v28, v28, v4, v5
	v_max_f32_e32 v25, v27, v25
	s_nop 0
	v_mov_b32_dpp v29, v28 quad_perm:[1,0,3,2] row_mask:0xf bank_mask:0xf
	ds_bpermute_b32 v27, v74, v25
	v_add_f32_e32 v26, v24, v26
	v_add_f32_e32 v77, v19, v26
	s_nop 1
	v_mov_b32_dpp v78, v77 quad_perm:[1,0,3,2] row_mask:0xf bank_mask:0xf
	s_waitcnt lgkmcnt(1)
	v_max_f32_e32 v29, v29, v29
	s_waitcnt lgkmcnt(0)
	v_max_f32_e32 v26, v27, v27
	v_max_f32_e32 v76, v28, v29
	v_max_f32_e32 v25, v25, v26
	s_nop 0
	v_mov_b32_dpp v79, v76 quad_perm:[2,3,0,1] row_mask:0xf bank_mask:0xf
	v_cmp_neq_f32_e64 s[8:9], s39, v25
	s_waitcnt lgkmcnt(0)
	v_add_f32_e32 v77, v77, v78
	s_nop 1
	v_mov_b32_dpp v78, v77 quad_perm:[2,3,0,1] row_mask:0xf bank_mask:0xf
	v_cndmask_b32_e64 v67, 0, v25, s[8:9]
	v_sub_f32_e32 v25, v130, v67
	v_exp_f32_e32 v25, v25
	v_sub_f32_e32 v26, v131, v67
	v_exp_f32_e32 v26, v26
	v_sub_f32_e32 v27, v132, v67
	s_waitcnt lgkmcnt(0)
	v_max_f32_e32 v79, v79, v79
	v_exp_f32_e32 v27, v27
	v_sub_f32_e32 v28, v129, v67
	v_max_f32_e32 v76, v76, v79
	v_exp_f32_e32 v29, v28
	v_sub_f32_e32 v28, v82, v67
	v_mov_b32_dpp v79, v76 row_half_mirror row_mask:0xf bank_mask:0xf
	v_add_f32_e32 v66, 0, v25
	v_exp_f32_e32 v28, v28
	v_add_f32_e32 v66, v26, v66
	v_add_f32_e32 v66, v27, v66
	v_add_f32_e32 v66, v29, v66
	v_add_f32_e32 v80, v28, v66
	s_waitcnt lgkmcnt(0)
	v_max_f32_e32 v66, v79, v79
	v_max_f32_e32 v76, v76, v66
	s_nop 1
	v_mov_b32_dpp v79, v76 row_mirror row_mask:0xf bank_mask:0xf
	v_sub_f32_e32 v7, v7, v67
	v_exp_f32_e32 v66, v7
	v_sub_f32_e32 v7, v8, v67
	v_sub_f32_e32 v6, v6, v67
	s_waitcnt lgkmcnt(0)
	v_max_f32_e32 v8, v79, v79
	v_max_f32_e32 v8, v76, v8
	ds_bpermute_b32 v67, v74, v8
	v_exp_f32_e32 v6, v6
	v_exp_f32_e32 v7, v7
	v_add_f32_e32 v77, v77, v78
	s_nop 1
	v_mov_b32_dpp v78, v77 row_half_mirror row_mask:0xf bank_mask:0xf
	s_waitcnt lgkmcnt(0)
	v_max_f32_e32 v67, v67, v67
	v_max_f32_e32 v8, v8, v67
	v_cmp_neq_f32_e64 s[8:9], s39, v8
	v_add_f32_e32 v76, v6, v80
	v_add_f32_e32 v76, v66, v76
	v_cndmask_b32_e64 v81, 0, v8, s[8:9]
	v_sub_f32_e32 v8, v33, v81
	v_exp_f32_e32 v8, v8
	v_sub_f32_e32 v33, v126, v81
	v_exp_f32_e32 v33, v33
	v_sub_f32_e32 v67, v127, v81
	v_add_f32_e32 v79, v7, v76
	v_exp_f32_e32 v67, v67
	v_sub_f32_e32 v76, v128, v81
	v_exp_f32_e32 v76, v76
	v_sub_f32_e32 v2, v2, v81
	v_add_f32_e32 v82, 0, v8
	v_exp_f32_e32 v2, v2
	v_sub_f32_e32 v3, v3, v81
	v_add_f32_e32 v82, v33, v82
	v_exp_f32_e32 v3, v3
	v_sub_f32_e32 v4, v4, v81
	v_add_f32_e32 v82, v67, v82
	v_exp_f32_e32 v4, v4
	v_sub_f32_e32 v5, v5, v81
	v_add_f32_e32 v82, v76, v82
	v_exp_f32_e32 v5, v5
	v_add_f32_e32 v81, v2, v82
	v_add_f32_e32 v81, v3, v81
	v_add_f32_e32 v81, v4, v81
	v_add_f32_e32 v81, v5, v81
	v_mov_b32_dpp v80, v79 quad_perm:[1,0,3,2] row_mask:0xf bank_mask:0xf
	s_nop 0
	v_mov_b32_dpp v70, v81 quad_perm:[1,0,3,2] row_mask:0xf bank_mask:0xf
	ds_bpermute_b32 v69, v75, v68
	s_waitcnt lgkmcnt(1)
	v_add_f32_e32 v79, v79, v80
	s_waitcnt lgkmcnt(1)
	v_add_f32_e32 v70, v81, v70
	v_mov_b32_dpp v80, v79 quad_perm:[2,3,0,1] row_mask:0xf bank_mask:0xf
	s_nop 0
	v_mov_b32_dpp v71, v70 quad_perm:[2,3,0,1] row_mask:0xf bank_mask:0xf
	s_waitcnt lgkmcnt(0)
	v_add_f32_e32 v79, v79, v80
	s_waitcnt lgkmcnt(0)
	v_add_f32_e32 v70, v70, v71
	v_mov_b32_dpp v80, v79 row_half_mirror row_mask:0xf bank_mask:0xf
	s_nop 0
	v_mov_b32_dpp v71, v70 row_half_mirror row_mask:0xf bank_mask:0xf
	v_add_f32_e32 v72, v77, v78
	s_nop 1
	v_mov_b32_dpp v77, v72 row_mirror row_mask:0xf bank_mask:0xf
	s_waitcnt lgkmcnt(0)
	v_add_f32_e32 v78, v79, v80
	s_waitcnt lgkmcnt(0)
	v_add_f32_e32 v70, v70, v71
	v_mov_b32_dpp v79, v78 row_mirror row_mask:0xf bank_mask:0xf
	s_nop 0
	v_mov_b32_dpp v71, v70 row_mirror row_mask:0xf bank_mask:0xf
	s_waitcnt lgkmcnt(0)
	v_add_f32_e32 v72, v72, v77
	ds_bpermute_b32 v73, v74, v72
	s_waitcnt lgkmcnt(1)
	v_add_f32_e32 v77, v78, v79
	s_waitcnt lgkmcnt(1)
	v_add_f32_e32 v79, v70, v71
	ds_bpermute_b32 v78, v74, v77
	ds_bpermute_b32 v74, v74, v79
	s_waitcnt lgkmcnt(2)
	v_add_f32_e32 v70, v72, v73
	ds_bpermute_b32 v71, v75, v70
	s_waitcnt lgkmcnt(2)
	v_add_f32_e32 v72, v77, v78
	s_waitcnt lgkmcnt(1)
	v_add_f32_e32 v74, v79, v74
	ds_bpermute_b32 v73, v75, v72
	ds_bpermute_b32 v75, v75, v74
	s_and_saveexec_b64 s[8:9], s[6:7]
	s_cbranch_execz .LBB0_4489
	v_readlane_b32 s4, v255, 27
	v_cvt_pk_bf16_f32 v9, v9, v149
	s_nop 1
	v_lshl_add_u32 v77, v30, 1, s4
	ds_write_b16 v77, v9
	v_cvt_pk_bf16_f32 v9, v10, v149
	ds_write_b16 v77, v9 offset:64
	v_cvt_pk_bf16_f32 v9, v11, v149
	ds_write_b16 v77, v9 offset:128
	v_cvt_pk_bf16_f32 v9, v12, v149
	ds_write_b16 v77, v9 offset:192
	v_cvt_pk_bf16_f32 v9, v13, v149
	ds_write_b16 v77, v9 offset:256
	v_cvt_pk_bf16_f32 v9, v14, v149
	ds_write_b16 v77, v9 offset:320
	v_cvt_pk_bf16_f32 v9, v15, v149
	ds_write_b16 v77, v9 offset:384
	v_cvt_pk_bf16_f32 v9, v16, v149
	ds_write_b16 v77, v9 offset:448
	v_cvt_pk_bf16_f32 v9, v17, v149
	ds_write_b16 v77, v9 offset:512
	v_cvt_pk_bf16_f32 v9, v18, v149
	ds_write_b16 v77, v9 offset:576
	v_cvt_pk_bf16_f32 v9, v21, v149
	ds_write_b16 v77, v9 offset:640
	v_cvt_pk_bf16_f32 v9, v20, v149
	ds_write_b16 v77, v9 offset:704
	v_cvt_pk_bf16_f32 v9, v23, v149
	ds_write_b16 v77, v9 offset:768
	v_cvt_pk_bf16_f32 v9, v22, v149
	ds_write_b16 v77, v9 offset:832
	v_cvt_pk_bf16_f32 v9, v24, v149
	ds_write_b16 v77, v9 offset:896
	v_cvt_pk_bf16_f32 v9, v19, v149
	ds_write_b16 v77, v9 offset:960
	v_cvt_pk_bf16_f32 v9, v25, v149
	ds_write_b16 v77, v9 offset:1024
	v_cvt_pk_bf16_f32 v9, v26, v149
	ds_write_b16 v77, v9 offset:1088
	v_cvt_pk_bf16_f32 v9, v27, v149
	ds_write_b16 v77, v9 offset:1152
	v_cvt_pk_bf16_f32 v9, v29, v149
	ds_write_b16 v77, v9 offset:1216
	v_cvt_pk_bf16_f32 v9, v28, v149
	ds_write_b16 v77, v9 offset:1280
	v_cvt_pk_bf16_f32 v6, v6, v149
	ds_write_b16 v77, v6 offset:1344
	v_cvt_pk_bf16_f32 v6, v66, v149
	ds_write_b16 v77, v6 offset:1408
	v_cvt_pk_bf16_f32 v6, v7, v149
	ds_write_b16 v77, v6 offset:1472
	v_cvt_pk_bf16_f32 v6, v8, v149
	ds_write_b16 v77, v6 offset:1536
	v_cvt_pk_bf16_f32 v6, v33, v149
	ds_write_b16 v77, v6 offset:1600
	v_cvt_pk_bf16_f32 v6, v67, v149
	ds_write_b16 v77, v6 offset:1664
	v_cvt_pk_bf16_f32 v6, v76, v149
	ds_write_b16 v77, v6 offset:1728
	v_cvt_pk_bf16_f32 v2, v2, v149
	ds_write_b16 v77, v2 offset:1792
	v_cvt_pk_bf16_f32 v2, v3, v149
	ds_write_b16 v77, v2 offset:1856
	v_cvt_pk_bf16_f32 v2, v4, v149
	ds_write_b16 v77, v2 offset:1920
	v_cvt_pk_bf16_f32 v2, v5, v149
	ds_write_b16 v77, v2 offset:1984
